# attention chunk loop: K/V global loads issued two chunks ahead (two staging register sets, loop unrolled by two) instead of one
# speedup vs baseline: 1.0011x; 1.0011x over previous
; #define LAS __attribute__((address_space(3)))
; __device__ __forceinline__ void lds_barrier() { asm volatile("s_waitcnt lgkmcnt(0)" ::: "memory"); __builtin_amdgcn_s_barrier(); asm volatile("" ::: "memory"); }
; __device__ __forceinline__ int opaque_tid() { int t = threadIdx.x; asm volatile("" : "+v"(t)); return t; }
; #define ATT_LOAD(jj_) do { const bf16_t* kb_ = zb + (size_t)((c - 8 + (jj_)) * 64 + skey) * ZLD + hp * 128 + spc * 8; \
;         kr[0] = *(const u32x4*)(kb_ + 256); vr[0] = *(const u32x4*)(kb_ + 512); kr[1] = *(const u32x4*)(kb_ + (size_t)32 * ZLD + 256); vr[1] = *(const u32x4*)(kb_ + (size_t)32 * ZLD + 512); } while (0)
; __device__ __forceinline__ void attn_item(const Params& p, int l, int item, LAS unsigned char* lds) {
;     const int tid = opaque_tid(), wid = tid >> 6, lane = tid & 63, fr = lane & 15, fq = lane >> 4;
;     const int b = item >> 6, c = (item >> 1) & 31, hp = item & 1;
;     const int hh = wid >> 2, head = hp * 2 + hh, q0 = (wid & 3) * 16;
;     constexpr int KST = 272, VST = 288, KBUF = 64 * KST, BUFB = KBUF + 64 * VST;
;     LAS float* bias_s = (LAS float*)(lds + 2 * BUFB);
;     const bf16_t* zb = p.z + (size_t)b * SEQ * ZLD;
;     lds_barrier();
;     for (int i = tid; i < 640; i += 512) { const int h2 = i / 320, idx = i - h2 * 320; bias_s[i] = p.rel_bias[((size_t)l * 4 + hp * 2 + h2) * 320 + idx] * LOG2E; }
;     const bf16_t* qp = zb + (size_t)(c * 64 + q0 + fr) * ZLD + head * 64 + fq * 8;
;     const bf16x8 qf0 = *(const bf16x8*)qp, qf1 = *(const bf16x8*)(qp + 32);
;     f32x4 o[4];
; #pragma unroll
;     for (int dt = 0; dt < 4; ++dt) o[dt] = ZERO4;
;     float mrun = -1e30f, lsum = 0.f;
;     const int jj0 = c >= 8 ? 0 : 8 - c;
;     const int skey = tid >> 4, spc = tid & 15;
;     u32x4 kr[2], vr[2];
;     ...
;     ATT_LOAD(jj0);
;     for (int jj = jj0; jj <= 8; ++jj) {
;         LAS unsigned char* Kb = lds + (jj & 1) * BUFB; LAS unsigned char* Vb = Kb + KBUF;
;         *(LAS u32x4*)(Kb + skey * KST + spc * 16) = kr[0]; *(LAS u32x4*)(Kb + (skey + 32) * KST + spc * 16) = kr[1];
;         *(LAS u32x4*)(Vb + skey * VST + spc * 16) = vr[0]; *(LAS u32x4*)(Vb + (skey + 32) * VST + spc * 16) = vr[1];
;         if (jj < 8) ATT_LOAD(jj + 1);
.LBB0_409:
	s_or_b64 exec, exec, s[4:5]
	s_add_i32 s4, s69, 0xffffff00
	s_ashr_i32 s4, s4, 6
	s_bfe_u32 s22, s42, 0x50001
	v_lshrrev_b32_e32 v0, 2, v28
	s_ashr_i32 s5, s4, 31
	s_mul_i32 s7, s4, 0xb00000
	v_and_b32_e32 v3, 15, v28
	v_and_b32_e32 v58, 48, v0
	s_mul_hi_i32 s6, s4, 0xb00000
	s_add_u32 s16, s8, s7
	s_addc_u32 s17, s9, s6
	s_lshl_b32 s6, s22, 6
	v_or_b32_e32 v31, v58, v3
	s_sub_i32 s7, 8, s22
	v_or_b32_e32 v0, s6, v31
	s_cmp_lt_u32 s22, 8
	v_mul_u32_u24_e32 v0, 0xb00, v0
	s_cselect_b32 s7, s7, 0
	v_ashrrev_i32_e32 v30, 8, v28
	v_lshlrev_b32_e32 v0, 1, v0
	v_mov_b32_e32 v1, v2
	s_add_i32 s22, s22, s7
	v_lshl_add_u64 v[4:5], s[16:17], 0, v[0:1]
	v_add_lshl_u32 v0, v30, s15, 6
	s_lshl_b32 s15, s22, 6
	v_ashrrev_i32_e32 v32, 4, v28
	s_addk_i32 s15, 0xfe00
	v_add_u32_e32 v14, s15, v32
	v_mov_b64_e32 v[12:13], s[16:17]
	s_movk_i32 s22, 0x1600
	v_mad_i64_i32 v[12:13], s[16:17], v14, s22, v[12:13]
	s_mov_b32 s15, s43
	s_lshl_b32 s14, s14, 8
	v_lshl_add_u64 v[12:13], v[12:13], 0, s[14:15]
	v_lshlrev_b32_e32 v54, 4, v3
	v_mov_b32_e32 v55, v2
	v_bfe_u32 v29, v28, 4, 2
	v_ashrrev_i32_e32 v1, 31, v0
	v_lshl_add_u64 v[20:21], v[12:13], 0, v[54:55]
	s_mov_b32 s14, 0x2c000
	v_lshl_add_u64 v[4:5], v[0:1], 1, v[4:5]
	v_lshlrev_b32_e32 v52, 4, v29
	v_mov_b32_e32 v53, v2
	v_add_co_u32_e32 v24, vcc, s14, v20
	v_lshl_add_u64 v[8:9], v[4:5], 0, v[52:53]
	s_nop 0
	v_addc_co_u32_e32 v25, vcc, 0, v21, vcc
	global_load_dwordx4 v[4:7], v[8:9], off
	s_nop 0
	global_load_dwordx4 v[8:11], v[8:9], off offset:64
	s_nop 0
	global_load_dwordx4 v[12:15], v[20:21], off offset:512
	global_load_dwordx4 v[16:19], v[20:21], off offset:1024
	s_nop 0
	global_load_dwordx4 v[20:23], v[24:25], off offset:512
	s_nop 0
	global_load_dwordx4 v[24:27], v[24:25], off offset:1024
	s_movk_i32 s15, 0x110
	v_mul_lo_u32 v55, v32, s15
	s_movk_i32 s15, 0x120
	v_mul_lo_u32 v60, v32, s15
	v_readlane_b32 s15, v255, 10
	v_lshlrev_b32_e32 v53, 2, v29
	v_bfe_u32 v29, v28, 2, 2
	v_mov_b32_e32 v33, s15
	s_add_i32 s15, s39, s95
	s_add_i32 s15, s15, s96
	s_bfe_u32 s15, s15, 0x50001
	v_lshlrev_b32_e32 v28, 3, v28
	s_add_i32 s15, s7, s15
	v_and_b32_e32 v64, 24, v28
	v_lshl_add_u32 v28, s15, 6, v32
	v_or_b32_e32 v29, v53, v29
	v_add_u32_e32 v28, 0xfffffe40, v28
	v_mul_u32_u24_e32 v66, 0x120, v29
	v_mad_i64_i32 v[28:29], s[16:17], v28, s22, 0
	v_mad_i64_i32 v[28:29], s[16:17], s4, v212, v[28:29]
	s_and_b32 s0, s0, 0x100
	v_or3_b32 v28, v28, s0, v54
	v_lshl_add_u64 v[28:29], s[8:9], 0, v[28:29]
	s_mov_b64 s[16:17], 0x2c400
	v_lshl_add_u64 v[56:57], v[28:29], 0, s[16:17]
	v_sub_u32_e32 v28, v31, v53
	s_lshl_b32 s0, s7, 6
	v_mov_b32_e32 v68, 0
	s_mov_b32 s14, 0
	v_add_u32_e32 v59, 0x2200, v55
	v_add_u32_e32 v61, 0x2400, v60
	v_lshlrev_b32_e32 v62, 7, v30
	v_mad_i32_i24 v63, v30, s31, v33
	v_mul_u32_u24_e32 v65, 0x110, v3
	v_subrev_u32_e32 v67, s0, v28
	s_addk_i32 s0, 0xfe00
	v_mov_b32_e32 v70, 0xf149f2ca
	v_mov_b32_e32 v28, 0
	v_mov_b32_e32 v29, v68
	v_mov_b32_e32 v30, v68
	v_mov_b32_e32 v31, v68
	v_mov_b32_e32 v32, 0
	v_mov_b32_e32 v33, v68
	v_mov_b32_e32 v34, v68
	v_mov_b32_e32 v35, v68
	v_mov_b32_e32 v36, 0
	v_mov_b32_e32 v37, v68
	v_mov_b32_e32 v38, v68
	v_mov_b32_e32 v39, v68
	v_mov_b32_e32 v40, 0
	v_mov_b32_e32 v41, v68
	v_mov_b32_e32 v42, v68
	v_mov_b32_e32 v43, v68
	s_cmp_lt_u32 s7, 8
	s_cbranch_scc0 .LBB0_410
	v_add_co_u32_e32 v236, vcc, 0xfffd4000, v56
	s_nop 1
	v_addc_co_u32_e32 v237, vcc, -1, v57, vcc
	global_load_dwordx4 v[220:223], v[236:237], off offset:-512
	global_load_dwordx4 v[224:227], v[236:237], off
	global_load_dwordx4 v[228:231], v[56:57], off offset:-512
	global_load_dwordx4 v[232:235], v[56:57], off
.LBB0_410:
	s_bitcmp1_b32 s7, 0
	s_cselect_b32 s15, 0x8c00, 0
	s_cmp_lt_u32 s7, 8
	s_cbranch_scc0 .Lattn_toplast_c0
	v_add3_u32 v44, s15, v55, v54
	s_waitcnt vmcnt(7)
	ds_write_b128 v44, v[12:15]
	v_add3_u32 v44, s15, v59, v54
	s_waitcnt vmcnt(5)
	ds_write_b128 v44, v[20:23]
	v_add3_u32 v44, s15, v60, v54
	ds_write_b128 v44, v[16:19] offset:17408
	v_add3_u32 v44, s15, v61, v54
	s_waitcnt vmcnt(4)
	ds_write_b128 v44, v[24:27] offset:17408
	s_branch .Lattn_topjoin_c0
.Lattn_toplast_c0:
	v_add3_u32 v44, s15, v55, v54
	s_waitcnt vmcnt(3)
	ds_write_b128 v44, v[12:15]
	v_add3_u32 v44, s15, v59, v54
	s_waitcnt vmcnt(1)
	ds_write_b128 v44, v[20:23]
	v_add3_u32 v44, s15, v60, v54
	ds_write_b128 v44, v[16:19] offset:17408
	v_add3_u32 v44, s15, v61, v54
	s_waitcnt vmcnt(0)
	ds_write_b128 v44, v[24:27] offset:17408
.Lattn_topjoin_c0:
	s_cmp_le_u32 s7, 6
	s_cbranch_scc0 .Lattn_412_c0
	v_add_co_u32_e32 v218, vcc, 0x58000, v56
	s_nop 1
	v_addc_co_u32_e32 v219, vcc, 0, v57, vcc
	v_add_co_u32_e32 v236, vcc, 0x2c000, v56
	s_nop 1
	v_addc_co_u32_e32 v237, vcc, 0, v57, vcc
	global_load_dwordx4 v[12:15], v[236:237], off offset:-512
	global_load_dwordx4 v[16:19], v[236:237], off
	global_load_dwordx4 v[20:23], v[218:219], off offset:-512
	global_load_dwordx4 v[24:27], v[218:219], off

; #define LAS __attribute__((address_space(3)))
; #define ATT_LOAD(jj_) do { const bf16_t* kb_ = zb + (size_t)((c - 8 + (jj_)) * 64 + skey) * ZLD + hp * 128 + spc * 8; \
;         kr[0] = *(const u32x4*)(kb_ + 256); vr[0] = *(const u32x4*)(kb_ + 512); kr[1] = *(const u32x4*)(kb_ + (size_t)32 * ZLD + 256); vr[1] = *(const u32x4*)(kb_ + (size_t)32 * ZLD + 512); } while (0)
; __device__ __forceinline__ void attn_item(const Params& p, int l, int item, LAS unsigned char* lds) {
;     ...
;         LAS unsigned char* Kb = lds + (jj & 1) * BUFB; LAS unsigned char* Vb = Kb + KBUF;
;         *(LAS u32x4*)(Kb + skey * KST + spc * 16) = kr[0]; *(LAS u32x4*)(Kb + (skey + 32) * KST + spc * 16) = kr[1];
;         *(LAS u32x4*)(Vb + skey * VST + spc * 16) = vr[0]; *(LAS u32x4*)(Vb + (skey + 32) * VST + spc * 16) = vr[1];
;         if (jj < 8) ATT_LOAD(jj + 1);
.Lattn_c1:
	s_bitcmp1_b32 s7, 0
	s_cselect_b32 s15, 0x8c00, 0
	s_cmp_lt_u32 s7, 8
	s_cbranch_scc0 .Lattn_toplast_c1
	v_add3_u32 v44, s15, v55, v54
	s_waitcnt vmcnt(7)
	ds_write_b128 v44, v[220:223]
	v_add3_u32 v44, s15, v59, v54
	s_waitcnt vmcnt(5)
	ds_write_b128 v44, v[228:231]
	v_add3_u32 v44, s15, v60, v54
	ds_write_b128 v44, v[224:227] offset:17408
	v_add3_u32 v44, s15, v61, v54
	s_waitcnt vmcnt(4)
	ds_write_b128 v44, v[232:235] offset:17408
	s_branch .Lattn_topjoin_c1
.Lattn_toplast_c1:
	v_add3_u32 v44, s15, v55, v54
	s_waitcnt vmcnt(3)
	ds_write_b128 v44, v[220:223]
	v_add3_u32 v44, s15, v59, v54
	s_waitcnt vmcnt(1)
	ds_write_b128 v44, v[228:231]
	v_add3_u32 v44, s15, v60, v54
	ds_write_b128 v44, v[224:227] offset:17408
	v_add3_u32 v44, s15, v61, v54
	s_waitcnt vmcnt(0)
	ds_write_b128 v44, v[232:235] offset:17408
.Lattn_topjoin_c1:
	s_cmp_le_u32 s7, 6
	s_cbranch_scc0 .Lattn_412_c1
	v_add_co_u32_e32 v218, vcc, 0x58000, v56
	s_nop 1
	v_addc_co_u32_e32 v219, vcc, 0, v57, vcc
	v_add_co_u32_e32 v236, vcc, 0x2c000, v56
	s_nop 1
	v_addc_co_u32_e32 v237, vcc, 0, v57, vcc
	global_load_dwordx4 v[220:223], v[236:237], off offset:-512
	global_load_dwordx4 v[224:227], v[236:237], off
	global_load_dwordx4 v[228:231], v[218:219], off offset:-512
	global_load_dwordx4 v[232:235], v[218:219], off
